# lever 6 (LDS bank conflicts): 36-byte rows for the selected-block bias table so the four lane groups of a table read hit disjoint banks
# speedup vs baseline: 1.0013x; 1.0013x over previous
.Lsel_lut:
	v_lshrrev_b32_e32 v67, 3, v66
	v_add_u32_e32 v67, 0xffffffc0, v67
	v_and_b32_e32 v144, 7, v66
	v_max_i32_e32 v145, 0, v67
	v_cvt_f32_u32_e32 v143, v145
	v_mul_f32_e32 v143, 0x3d800000, v143
	v_log_f32_e32 v143, v143
	s_nop 0
	v_mul_f32_e32 v143, 0x40124925, v143
	v_cvt_i32_f32_e32 v143, v143
	v_med3_i32 v143, v143, 0, 15
	v_add_u32_e32 v143, 16, v143
	v_cmp_gt_u32_e32 vcc, 16, v145
	s_nop 1
	v_cndmask_b32_e32 v143, v143, v145, vcc
	v_lshl_add_u32 v143, v143, 4, v144
	v_add_u32_e32 v143, s63, v143
	v_lshl_add_u32 v143, v143, 2, s57
	ds_read_b32 v143, v143
	v_cmp_le_i32_e32 vcc, 0, v67
	s_waitcnt lgkmcnt(0)
	v_mul_f32_e32 v143, 0x3fb8aa3b, v143
	v_cndmask_b32_e32 v143, v179, v143, vcc
	v_lshrrev_b32_e32 v177, 3, v66
	v_mul_u32_u24_e32 v177, 9, v177
	v_add_u32_e32 v177, v177, v144
	v_lshlrev_b32_e32 v177, 2, v177
	v_add_u32_e32 v177, 0xc000, v177
	ds_write_b32 v177, v143
	v_add_u32_e32 v66, 0x200, v66
	s_add_i32 s0, s0, -1
	s_cmp_lg_u32 s0, 0
	s_cbranch_scc1 .Lsel_lut
	s_waitcnt lgkmcnt(0)
	v_readfirstlane_b32 s1, v220
	s_waitcnt lgkmcnt(0)
	s_barrier
	s_and_b32 s0, s1, 3
	s_lshl_b32 s0, s0, 12
	s_cmp_lt_u32 s1, 4
	s_cselect_b32 s40, s18, s16
	s_cselect_b32 s41, s19, s17
	s_cselect_b32 s2, 1, 2
	s_lshl_b32 s2, s2, 14
	s_add_i32 s2, s2, s0
	s_add_i32 s62, s61, -1
	s_lshl_b32 s62, s62, 13
	s_add_i32 s0, s0, s62
	s_ashr_i32 s62, s0, 31
	s_add_u32 s40, s40, s0
	s_addc_u32 s41, s41, s62
	s_add_i32 m0, s2, 0
	s_nop 0
	global_load_lds_dwordx4 v140, s[40:41]
	s_add_i32 m0, s2, 1024
	s_add_u32 s40, s40, 0x400
	s_addc_u32 s41, s41, 0
	global_load_lds_dwordx4 v140, s[40:41]
	s_add_i32 m0, s2, 2048
	s_add_u32 s40, s40, 0x400
	s_addc_u32 s41, s41, 0
	global_load_lds_dwordx4 v140, s[40:41]
	s_add_i32 m0, s2, 3072
	s_add_u32 s40, s40, 0x400
	s_addc_u32 s41, s41, 0
	global_load_lds_dwordx4 v140, s[40:41]
	s_waitcnt vmcnt(0)
	s_barrier
	s_lshl_b32 s0, s26, 7
	s_add_u32 s38, s12, s0
	s_addc_u32 s39, s13, 0
	v_lshrrev_b32_e32 v144, 3, v199
	global_load_dword v176, v144, s[38:39]
	s_lshl_b32 s0, s26, 11
	s_add_u32 s54, s14, s0
	s_addc_u32 s55, s15, 0
	v_lshlrev_b32_e32 v67, 7, v202
	v_lshl_add_u32 v67, v198, 1, v67
	global_load_dwordx4 v[16:19], v67, s[54:55]
	global_load_dwordx4 v[20:23], v67, s[54:55] offset:64
	s_mov_b64 s[34:35], s[18:19]
	s_mov_b64 s[36:37], s[16:17]
	ds_read_b128 v[32:35], v140 offset:0
	ds_read_b128 v[36:39], v140 offset:1024
	ds_read_b128 v[40:43], v140 offset:2048
	ds_read_b128 v[44:47], v140 offset:3072
	ds_read_b128 v[48:51], v140 offset:4096
	ds_read_b128 v[52:55], v140 offset:5120
	ds_read_b128 v[56:59], v140 offset:6144
	ds_read_b128 v[60:63], v140 offset:7168
	ds_read_b128 v[100:103], v140 offset:8192
	ds_read_b128 v[104:107], v140 offset:9216
	ds_read_b128 v[108:111], v140 offset:10240
	ds_read_b128 v[112:115], v140 offset:11264
	ds_read_b128 v[116:119], v140 offset:12288
	ds_read_b128 v[120:123], v140 offset:13312
	ds_read_b128 v[124:127], v140 offset:14336
	ds_read_b128 v[128:131], v140 offset:15360
	s_lshr_b32 s0, s26, 6
	s_add_i32 s0, s0, 1
	s_min_i32 s28, s0, 16
	s_mov_b32 s29, 0
	s_mov_b32 s30, 0
	s_mov_b32 s51, 0
	v_mov_b32_e32 v196, 0xf149f2ca
	v_mov_b32_e32 v197, 0
	v_mov_b32_e32 v0, 0
	v_mov_b32_e32 v1, 0
	v_mov_b32_e32 v2, 0
	v_mov_b32_e32 v3, 0
	v_mov_b32_e32 v4, 0
	v_mov_b32_e32 v5, 0
	v_mov_b32_e32 v6, 0
	v_mov_b32_e32 v7, 0
	v_mov_b32_e32 v8, 0
	v_mov_b32_e32 v9, 0
	v_mov_b32_e32 v10, 0
	v_mov_b32_e32 v11, 0
	v_mov_b32_e32 v12, 0
	v_mov_b32_e32 v13, 0
	v_mov_b32_e32 v14, 0
	v_mov_b32_e32 v15, 0
	s_waitcnt lgkmcnt(0)
	v_mul_f32_e32 v178, 0x3fb8aa3b, v178
	s_waitcnt vmcnt(2)

.Lsel_slow:
	s_add_i32 s1, s0, 13
	s_mul_i32 s1, s1, 36
	s_add_i32 s1, s1, 0xc000
	v_mul_u32_u24_e32 v66, 36, v182
	v_sub_u32_e32 v66, s1, v66
	v_lshl_add_u32 v66, v200, 2, v66
	ds_read_b32 v222, v66 offset:1836
	ds_read_b32 v223, v66 offset:1800
	ds_read_b32 v224, v66 offset:1764
	ds_read_b32 v225, v66 offset:1728
	ds_read_b32 v226, v66 offset:1260
	ds_read_b32 v227, v66 offset:1224
	ds_read_b32 v228, v66 offset:1188
	ds_read_b32 v229, v66 offset:1152
	ds_read_b32 v230, v66 offset:684
	ds_read_b32 v231, v66 offset:648
	ds_read_b32 v232, v66 offset:612
	ds_read_b32 v233, v66 offset:576
	ds_read_b32 v234, v66 offset:108
	ds_read_b32 v235, v66 offset:72
	ds_read_b32 v236, v66 offset:36
	ds_read_b32 v237, v66 offset:0
	s_waitcnt lgkmcnt(0)
	v_pk_fma_f32 v[184:185], v[184:185], s[48:49], v[222:223] op_sel_hi:[1,0,1]
	v_pk_fma_f32 v[186:187], v[186:187], s[48:49], v[224:225] op_sel_hi:[1,0,1]
	v_pk_fma_f32 v[188:189], v[188:189], s[48:49], v[226:227] op_sel_hi:[1,0,1]
	v_pk_fma_f32 v[190:191], v[190:191], s[48:49], v[228:229] op_sel_hi:[1,0,1]
	v_pk_fma_f32 v[192:193], v[192:193], s[48:49], v[230:231] op_sel_hi:[1,0,1]
	v_pk_fma_f32 v[194:195], v[194:195], s[48:49], v[232:233] op_sel_hi:[1,0,1]
	v_pk_fma_f32 v[172:173], v[172:173], s[48:49], v[234:235] op_sel_hi:[1,0,1]
	v_pk_fma_f32 v[174:175], v[174:175], s[48:49], v[236:237] op_sel_hi:[1,0,1]
	s_cmp_eq_u32 s51, 0
	s_cbranch_scc1 .Lsel_maxA
	s_branch .Lsel_maxB
